# PH8 output stores carry the nt (streaming) hint so they do not displace A/B tiles in L2; PH7 stores write-through
# speedup vs baseline: 1.0024x; 1.0008x over previous
; #define SBAR() __builtin_amdgcn_sched_barrier(0)
; __device__ __forceinline__ float fast_sigmoid(float x) { return __builtin_amdgcn_rcpf(1.0f + __builtin_amdgcn_exp2f(-1.4426950408889634f * x)); }
; __device__ __forceinline__ u32x4 pack8(const f32x4 a, const f32x4 b) { u32x4 w; w.x = cvt_pk_bf16(a[0], a[1]); w.y = cvt_pk_bf16(a[2], a[3]); w.z = cvt_pk_bf16(b[0], b[1]); w.w = cvt_pk_bf16(b[2], b[3]); return w; }
;     __device__ __forceinline__ void operator()(f32x4 (&acc)[2][2][4][2], const Unit& u, int wr, int wc, int fr, int fq) const {
;     ...
;         } else if constexpr (PH == 8) {
;             float rsv[8];
; #pragma unroll
;             for (int i = 0; i < 8; ++i) rsv[i] = P.ssq_h1_()[ROWOF(i >> 2, i & 3)];
;             SBAR();
; #pragma unroll
;             for (int ai = 0; ai < 2; ++ai)
; #pragma unroll
;                 for (int m = 0; m < 4; ++m) { const int row = ROWOF(ai, m); const float rs = rsqrtf(rsv[ai * 4 + m] * (1.0f / 2048.0f) + EPS);
;                     f32x4 g0 = acc[ai][0][m][0] * rs, g1 = acc[ai][0][m][1] * rs; const f32x4 u0 = acc[ai][1][m][0] * rs, u1 = acc[ai][1][m][1] * rs;
; #pragma unroll
;                     for (int j = 0; j < 4; ++j) { g0[j] = g0[j] * fast_sigmoid(g0[j]) * u0[j]; g1[j] = g1[j] * fast_sigmoid(g1[j]) * u1[j]; }
;                     *(u32x4*)(P.f_() + (size_t)row * DFF + u.pn * 128 + c8) = pack8(g0, g1); }
.LBB0_1002:
	v_lshl_add_u32 v146, s22, 8, v150
	v_ashrrev_i32_e32 v147, 31, v146
	v_lshl_add_u64 v[156:157], v[146:147], 2, s[10:11]
	global_load_dword v158, v[156:157], off
	global_load_dword v159, v[156:157], off offset:64
	global_load_dword v164, v[156:157], off offset:128
	global_load_dword v165, v[156:157], off offset:192
	global_load_dword v166, v[156:157], off offset:512
	global_load_dword v149, v[156:157], off offset:576
	global_load_dword v148, v[156:157], off offset:640
	global_load_dword v147, v[156:157], off offset:704
	v_add_u32_e32 v156, 0x80, v146
	s_waitcnt vmcnt(0)
	s_lshl_b32 s22, s23, 7
	s_ashr_i32 s23, s22, 31
	s_lshl_b64 s[22:23], s[22:23], 1
	s_add_u32 s98, s12, s22
	s_addc_u32 s99, s13, s23
	s_mov_b32 s36, 0xbfb8aa3b
	s_mov_b32 s37, 0xbfb8aa3b
	s_mov_b32 s38, 1.0
	s_mov_b32 s39, 1.0
	v_fmamk_f32 v228, v158, 0x3a000000, v155
	v_mul_f32_e32 v229, 0x4b800000, v228
	v_cmp_gt_f32_e32 vcc, s51, v228
	s_nop 1
	v_cndmask_b32_e32 v228, v228, v229, vcc
	v_mad_u32_u24 v157, v146, s52, v134
	v_rsq_f32_e32 v228, v228
	s_nop 0
	v_mul_f32_e32 v229, 0x45800000, v228
	s_nop 0
	v_cndmask_b32_e32 v228, v228, v229, vcc
	v_pk_mul_f32 v[126:127], v[126:127], v[228:229] op_sel_hi:[1,0]
	v_pk_mul_f32 v[128:129], v[128:129], v[228:229] op_sel_hi:[1,0]
	v_pk_mul_f32 v[122:123], v[122:123], v[228:229] op_sel_hi:[1,0]
	v_pk_mul_f32 v[124:125], v[124:125], v[228:229] op_sel_hi:[1,0]
	v_pk_mul_f32 v[118:119], v[118:119], v[228:229] op_sel_hi:[1,0]
	v_pk_mul_f32 v[120:121], v[120:121], v[228:229] op_sel_hi:[1,0]
	v_pk_mul_f32 v[114:115], v[114:115], v[228:229] op_sel_hi:[1,0]
	v_pk_mul_f32 v[116:117], v[116:117], v[228:229] op_sel_hi:[1,0]
	v_pk_mul_f32 v[220:221], v[126:127], s[36:37]
	v_pk_mul_f32 v[222:223], v[128:129], s[36:37]
	v_pk_mul_f32 v[224:225], v[122:123], s[36:37]
	v_pk_mul_f32 v[226:227], v[124:125], s[36:37]
	v_exp_f32_e32 v220, v220
	v_exp_f32_e32 v221, v221
	v_exp_f32_e32 v222, v222
	v_exp_f32_e32 v223, v223
	v_exp_f32_e32 v224, v224
	v_exp_f32_e32 v225, v225
	v_exp_f32_e32 v226, v226
	v_exp_f32_e32 v227, v227
	v_pk_add_f32 v[220:221], v[220:221], s[38:39]
	v_pk_add_f32 v[222:223], v[222:223], s[38:39]
	v_pk_add_f32 v[224:225], v[224:225], s[38:39]
	v_pk_add_f32 v[226:227], v[226:227], s[38:39]
	v_rcp_f32_e32 v220, v220
	v_rcp_f32_e32 v221, v221
	v_rcp_f32_e32 v222, v222
	v_rcp_f32_e32 v223, v223
	v_rcp_f32_e32 v224, v224
	v_rcp_f32_e32 v225, v225
	v_rcp_f32_e32 v226, v226
	v_rcp_f32_e32 v227, v227
	v_pk_mul_f32 v[126:127], v[126:127], v[220:221]
	v_pk_mul_f32 v[128:129], v[128:129], v[222:223]
	v_pk_mul_f32 v[122:123], v[122:123], v[224:225]
	v_pk_mul_f32 v[124:125], v[124:125], v[226:227]
	v_pk_mul_f32 v[118:119], v[118:119], v[126:127]
	v_pk_mul_f32 v[120:121], v[120:121], v[128:129]
	v_pk_mul_f32 v[114:115], v[114:115], v[122:123]
	v_pk_mul_f32 v[116:117], v[116:117], v[124:125]
	v_cvt_pk_bf16_f32 v126, v118, v119
	v_cvt_pk_bf16_f32 v127, v120, v121
	v_cvt_pk_bf16_f32 v128, v114, v115
	v_cvt_pk_bf16_f32 v129, v116, v117
	global_store_dwordx4 v157, v[126:129], s[98:99] nt
	v_fmamk_f32 v228, v159, 0x3a000000, v155
	v_mul_f32_e32 v229, 0x4b800000, v228
	v_cmp_gt_f32_e32 vcc, s51, v228
	v_or_b32_e32 v156, 0x10, v146
	s_nop 0
	v_cndmask_b32_e32 v228, v228, v229, vcc
	v_mad_u32_u24 v160, v156, s52, v134
	v_rsq_f32_e32 v228, v228
	s_nop 0
	v_mul_f32_e32 v229, 0x45800000, v228
	s_nop 0
	v_cndmask_b32_e32 v228, v228, v229, vcc
	v_pk_mul_f32 v[110:111], v[110:111], v[228:229] op_sel_hi:[1,0]
	v_pk_mul_f32 v[112:113], v[112:113], v[228:229] op_sel_hi:[1,0]
	v_pk_mul_f32 v[106:107], v[106:107], v[228:229] op_sel_hi:[1,0]
	v_pk_mul_f32 v[108:109], v[108:109], v[228:229] op_sel_hi:[1,0]
	v_pk_mul_f32 v[102:103], v[102:103], v[228:229] op_sel_hi:[1,0]
	v_pk_mul_f32 v[104:105], v[104:105], v[228:229] op_sel_hi:[1,0]
	v_pk_mul_f32 v[98:99], v[98:99], v[228:229] op_sel_hi:[1,0]
	v_pk_mul_f32 v[100:101], v[100:101], v[228:229] op_sel_hi:[1,0]
	v_pk_mul_f32 v[220:221], v[110:111], s[36:37]
	v_pk_mul_f32 v[222:223], v[112:113], s[36:37]
	v_pk_mul_f32 v[224:225], v[106:107], s[36:37]
	v_pk_mul_f32 v[226:227], v[108:109], s[36:37]
	v_exp_f32_e32 v220, v220
	v_exp_f32_e32 v221, v221
	v_exp_f32_e32 v222, v222
	v_exp_f32_e32 v223, v223
	v_exp_f32_e32 v224, v224
	v_exp_f32_e32 v225, v225
	v_exp_f32_e32 v226, v226
	v_exp_f32_e32 v227, v227
	v_pk_add_f32 v[220:221], v[220:221], s[38:39]
	v_pk_add_f32 v[222:223], v[222:223], s[38:39]
	v_pk_add_f32 v[224:225], v[224:225], s[38:39]
	v_pk_add_f32 v[226:227], v[226:227], s[38:39]
	v_rcp_f32_e32 v220, v220
	v_rcp_f32_e32 v221, v221
	v_rcp_f32_e32 v222, v222
	v_rcp_f32_e32 v223, v223
	v_rcp_f32_e32 v224, v224
	v_rcp_f32_e32 v225, v225
	v_rcp_f32_e32 v226, v226
	v_rcp_f32_e32 v227, v227
	v_pk_mul_f32 v[110:111], v[110:111], v[220:221]
	v_pk_mul_f32 v[112:113], v[112:113], v[222:223]
	v_pk_mul_f32 v[106:107], v[106:107], v[224:225]
	v_pk_mul_f32 v[108:109], v[108:109], v[226:227]
	v_pk_mul_f32 v[102:103], v[102:103], v[110:111]
	v_pk_mul_f32 v[104:105], v[104:105], v[112:113]
	v_pk_mul_f32 v[98:99], v[98:99], v[106:107]
	v_pk_mul_f32 v[100:101], v[100:101], v[108:109]
	v_cvt_pk_bf16_f32 v110, v102, v103
	v_cvt_pk_bf16_f32 v111, v104, v105
	v_cvt_pk_bf16_f32 v112, v98, v99
	v_cvt_pk_bf16_f32 v113, v100, v101
	global_store_dwordx4 v160, v[110:113], s[98:99] nt
	v_fmamk_f32 v228, v164, 0x3a000000, v155
	v_mul_f32_e32 v229, 0x4b800000, v228
	v_cmp_gt_f32_e32 vcc, s51, v228
	v_or_b32_e32 v156, 0x20, v146
	s_nop 0
	v_cndmask_b32_e32 v228, v228, v229, vcc
	v_mad_u32_u24 v157, v156, s52, v134
	v_rsq_f32_e32 v228, v228
	s_nop 0
	v_mul_f32_e32 v229, 0x45800000, v228
	s_nop 0
	v_cndmask_b32_e32 v228, v228, v229, vcc
; __device__ __forceinline__ float fast_sigmoid(float x) { return __builtin_amdgcn_rcpf(1.0f + __builtin_amdgcn_exp2f(-1.4426950408889634f * x)); }
; __device__ __forceinline__ u32x4 pack8(const f32x4 a, const f32x4 b) { u32x4 w; w.x = cvt_pk_bf16(a[0], a[1]); w.y = cvt_pk_bf16(a[2], a[3]); w.z = cvt_pk_bf16(b[0], b[1]); w.w = cvt_pk_bf16(b[2], b[3]); return w; }
;     __device__ __forceinline__ void operator()(f32x4 (&acc)[2][2][4][2], const Unit& u, int wr, int wc, int fr, int fq) const {
;     ...
;             for (int ai = 0; ai < 2; ++ai)
; #pragma unroll
;                 for (int m = 0; m < 4; ++m) { const int row = ROWOF(ai, m); const float rs = rsqrtf(rsv[ai * 4 + m] * (1.0f / 2048.0f) + EPS);
;                     f32x4 g0 = acc[ai][0][m][0] * rs, g1 = acc[ai][0][m][1] * rs; const f32x4 u0 = acc[ai][1][m][0] * rs, u1 = acc[ai][1][m][1] * rs;
; #pragma unroll
;                     for (int j = 0; j < 4; ++j) { g0[j] = g0[j] * fast_sigmoid(g0[j]) * u0[j]; g1[j] = g1[j] * fast_sigmoid(g1[j]) * u1[j]; }
;                     *(u32x4*)(P.f_() + (size_t)row * DFF + u.pn * 128 + c8) = pack8(g0, g1); }
	v_pk_mul_f32 v[94:95], v[94:95], v[228:229] op_sel_hi:[1,0]
	v_pk_mul_f32 v[96:97], v[96:97], v[228:229] op_sel_hi:[1,0]
	v_pk_mul_f32 v[90:91], v[90:91], v[228:229] op_sel_hi:[1,0]
	v_pk_mul_f32 v[92:93], v[92:93], v[228:229] op_sel_hi:[1,0]
	v_pk_mul_f32 v[86:87], v[86:87], v[228:229] op_sel_hi:[1,0]
	v_pk_mul_f32 v[88:89], v[88:89], v[228:229] op_sel_hi:[1,0]
	v_pk_mul_f32 v[82:83], v[82:83], v[228:229] op_sel_hi:[1,0]
	v_pk_mul_f32 v[84:85], v[84:85], v[228:229] op_sel_hi:[1,0]
	v_pk_mul_f32 v[220:221], v[94:95], s[36:37]
	v_pk_mul_f32 v[222:223], v[96:97], s[36:37]
	v_pk_mul_f32 v[224:225], v[90:91], s[36:37]
	v_pk_mul_f32 v[226:227], v[92:93], s[36:37]
	v_exp_f32_e32 v220, v220
	v_exp_f32_e32 v221, v221
	v_exp_f32_e32 v222, v222
	v_exp_f32_e32 v223, v223
	v_exp_f32_e32 v224, v224
	v_exp_f32_e32 v225, v225
	v_exp_f32_e32 v226, v226
	v_exp_f32_e32 v227, v227
	v_pk_add_f32 v[220:221], v[220:221], s[38:39]
	v_pk_add_f32 v[222:223], v[222:223], s[38:39]
	v_pk_add_f32 v[224:225], v[224:225], s[38:39]
	v_pk_add_f32 v[226:227], v[226:227], s[38:39]
	v_rcp_f32_e32 v220, v220
	v_rcp_f32_e32 v221, v221
	v_rcp_f32_e32 v222, v222
	v_rcp_f32_e32 v223, v223
	v_rcp_f32_e32 v224, v224
	v_rcp_f32_e32 v225, v225
	v_rcp_f32_e32 v226, v226
	v_rcp_f32_e32 v227, v227
	v_pk_mul_f32 v[94:95], v[94:95], v[220:221]
	v_pk_mul_f32 v[96:97], v[96:97], v[222:223]
	v_pk_mul_f32 v[90:91], v[90:91], v[224:225]
	v_pk_mul_f32 v[92:93], v[92:93], v[226:227]
	v_pk_mul_f32 v[86:87], v[86:87], v[94:95]
	v_pk_mul_f32 v[88:89], v[88:89], v[96:97]
	v_pk_mul_f32 v[82:83], v[82:83], v[90:91]
	v_pk_mul_f32 v[84:85], v[84:85], v[92:93]
	v_cvt_pk_bf16_f32 v94, v86, v87
	v_cvt_pk_bf16_f32 v95, v88, v89
	v_cvt_pk_bf16_f32 v96, v82, v83
	v_cvt_pk_bf16_f32 v97, v84, v85
	global_store_dwordx4 v157, v[94:97], s[98:99] nt
	v_fmamk_f32 v228, v165, 0x3a000000, v155
	v_mul_f32_e32 v229, 0x4b800000, v228
	v_cmp_gt_f32_e32 vcc, s51, v228
	v_or_b32_e32 v156, 0x30, v146
	s_nop 0
	v_cndmask_b32_e32 v228, v228, v229, vcc
	v_mad_u32_u24 v160, v156, s52, v134
	v_rsq_f32_e32 v228, v228
	s_nop 0
	v_mul_f32_e32 v229, 0x45800000, v228
	s_nop 0
	v_cndmask_b32_e32 v228, v228, v229, vcc
	v_pk_mul_f32 v[78:79], v[78:79], v[228:229] op_sel_hi:[1,0]
	v_pk_mul_f32 v[80:81], v[80:81], v[228:229] op_sel_hi:[1,0]
	v_pk_mul_f32 v[74:75], v[74:75], v[228:229] op_sel_hi:[1,0]
	v_pk_mul_f32 v[76:77], v[76:77], v[228:229] op_sel_hi:[1,0]
	v_pk_mul_f32 v[70:71], v[70:71], v[228:229] op_sel_hi:[1,0]
	v_pk_mul_f32 v[72:73], v[72:73], v[228:229] op_sel_hi:[1,0]
	v_pk_mul_f32 v[66:67], v[66:67], v[228:229] op_sel_hi:[1,0]
	v_pk_mul_f32 v[68:69], v[68:69], v[228:229] op_sel_hi:[1,0]
	v_pk_mul_f32 v[220:221], v[78:79], s[36:37]
	v_pk_mul_f32 v[222:223], v[80:81], s[36:37]
	v_pk_mul_f32 v[224:225], v[74:75], s[36:37]
	v_pk_mul_f32 v[226:227], v[76:77], s[36:37]
	v_exp_f32_e32 v220, v220
	v_exp_f32_e32 v221, v221
	v_exp_f32_e32 v222, v222
	v_exp_f32_e32 v223, v223
	v_exp_f32_e32 v224, v224
	v_exp_f32_e32 v225, v225
	v_exp_f32_e32 v226, v226
	v_exp_f32_e32 v227, v227
	v_pk_add_f32 v[220:221], v[220:221], s[38:39]
	v_pk_add_f32 v[222:223], v[222:223], s[38:39]
	v_pk_add_f32 v[224:225], v[224:225], s[38:39]
	v_pk_add_f32 v[226:227], v[226:227], s[38:39]
	v_rcp_f32_e32 v220, v220
	v_rcp_f32_e32 v221, v221
	v_rcp_f32_e32 v222, v222
	v_rcp_f32_e32 v223, v223
	v_rcp_f32_e32 v224, v224
	v_rcp_f32_e32 v225, v225
	v_rcp_f32_e32 v226, v226
	v_rcp_f32_e32 v227, v227
	v_pk_mul_f32 v[78:79], v[78:79], v[220:221]
	v_pk_mul_f32 v[80:81], v[80:81], v[222:223]
	v_pk_mul_f32 v[74:75], v[74:75], v[224:225]
	v_pk_mul_f32 v[76:77], v[76:77], v[226:227]
	v_pk_mul_f32 v[70:71], v[70:71], v[78:79]
	v_pk_mul_f32 v[72:73], v[72:73], v[80:81]
	v_pk_mul_f32 v[66:67], v[66:67], v[74:75]
	v_pk_mul_f32 v[68:69], v[68:69], v[76:77]
	v_cvt_pk_bf16_f32 v78, v70, v71
	v_cvt_pk_bf16_f32 v79, v72, v73
	v_cvt_pk_bf16_f32 v80, v66, v67
	v_cvt_pk_bf16_f32 v81, v68, v69
	global_store_dwordx4 v160, v[78:81], s[98:99] nt
	v_fmamk_f32 v228, v166, 0x3a000000, v155
	v_mul_f32_e32 v229, 0x4b800000, v228
	v_cmp_gt_f32_e32 vcc, s51, v228
	v_add_u32_e32 v156, 0x80, v146
	s_nop 0
	v_cndmask_b32_e32 v228, v228, v229, vcc
	v_mad_u32_u24 v157, v156, s52, v134
	v_rsq_f32_e32 v228, v228
	s_nop 0
	v_mul_f32_e32 v229, 0x45800000, v228
	s_nop 0
	v_cndmask_b32_e32 v228, v228, v229, vcc
	v_pk_mul_f32 v[62:63], v[62:63], v[228:229] op_sel_hi:[1,0]
	v_pk_mul_f32 v[64:65], v[64:65], v[228:229] op_sel_hi:[1,0]
	v_pk_mul_f32 v[58:59], v[58:59], v[228:229] op_sel_hi:[1,0]
	v_pk_mul_f32 v[60:61], v[60:61], v[228:229] op_sel_hi:[1,0]
	v_pk_mul_f32 v[54:55], v[54:55], v[228:229] op_sel_hi:[1,0]
	v_pk_mul_f32 v[56:57], v[56:57], v[228:229] op_sel_hi:[1,0]
	v_pk_mul_f32 v[50:51], v[50:51], v[228:229] op_sel_hi:[1,0]
	v_pk_mul_f32 v[52:53], v[52:53], v[228:229] op_sel_hi:[1,0]
	v_pk_mul_f32 v[220:221], v[62:63], s[36:37]
	v_pk_mul_f32 v[222:223], v[64:65], s[36:37]
	v_pk_mul_f32 v[224:225], v[58:59], s[36:37]
	v_pk_mul_f32 v[226:227], v[60:61], s[36:37]
	v_exp_f32_e32 v220, v220
	v_exp_f32_e32 v221, v221
	v_exp_f32_e32 v222, v222
	v_exp_f32_e32 v223, v223
	v_exp_f32_e32 v224, v224
	v_exp_f32_e32 v225, v225
	v_exp_f32_e32 v226, v226
	v_exp_f32_e32 v227, v227
	v_pk_add_f32 v[220:221], v[220:221], s[38:39]
	v_pk_add_f32 v[222:223], v[222:223], s[38:39]
	v_pk_add_f32 v[224:225], v[224:225], s[38:39]
	v_pk_add_f32 v[226:227], v[226:227], s[38:39]
	v_rcp_f32_e32 v220, v220
	v_rcp_f32_e32 v221, v221
	v_rcp_f32_e32 v222, v222
	v_rcp_f32_e32 v223, v223
	v_rcp_f32_e32 v224, v224
	v_rcp_f32_e32 v225, v225
	v_rcp_f32_e32 v226, v226
	v_rcp_f32_e32 v227, v227
	v_pk_mul_f32 v[62:63], v[62:63], v[220:221]
; __device__ __forceinline__ float fast_sigmoid(float x) { return __builtin_amdgcn_rcpf(1.0f + __builtin_amdgcn_exp2f(-1.4426950408889634f * x)); }
; __device__ __forceinline__ u32x4 pack8(const f32x4 a, const f32x4 b) { u32x4 w; w.x = cvt_pk_bf16(a[0], a[1]); w.y = cvt_pk_bf16(a[2], a[3]); w.z = cvt_pk_bf16(b[0], b[1]); w.w = cvt_pk_bf16(b[2], b[3]); return w; }
;     __device__ __forceinline__ void operator()(f32x4 (&acc)[2][2][4][2], const Unit& u, int wr, int wc, int fr, int fq) const {
;     ...
;             for (int ai = 0; ai < 2; ++ai)
; #pragma unroll
;                 for (int m = 0; m < 4; ++m) { const int row = ROWOF(ai, m); const float rs = rsqrtf(rsv[ai * 4 + m] * (1.0f / 2048.0f) + EPS);
;                     f32x4 g0 = acc[ai][0][m][0] * rs, g1 = acc[ai][0][m][1] * rs; const f32x4 u0 = acc[ai][1][m][0] * rs, u1 = acc[ai][1][m][1] * rs;
; #pragma unroll
;                     for (int j = 0; j < 4; ++j) { g0[j] = g0[j] * fast_sigmoid(g0[j]) * u0[j]; g1[j] = g1[j] * fast_sigmoid(g1[j]) * u1[j]; }
;                     *(u32x4*)(P.f_() + (size_t)row * DFF + u.pn * 128 + c8) = pack8(g0, g1); }
	v_pk_mul_f32 v[64:65], v[64:65], v[222:223]
	v_pk_mul_f32 v[58:59], v[58:59], v[224:225]
	v_pk_mul_f32 v[60:61], v[60:61], v[226:227]
	v_pk_mul_f32 v[54:55], v[54:55], v[62:63]
	v_pk_mul_f32 v[56:57], v[56:57], v[64:65]
	v_pk_mul_f32 v[50:51], v[50:51], v[58:59]
	v_pk_mul_f32 v[52:53], v[52:53], v[60:61]
	v_cvt_pk_bf16_f32 v62, v54, v55
	v_cvt_pk_bf16_f32 v63, v56, v57
	v_cvt_pk_bf16_f32 v64, v50, v51
	v_cvt_pk_bf16_f32 v65, v52, v53
	global_store_dwordx4 v157, v[62:65], s[98:99] nt
	v_fmamk_f32 v228, v149, 0x3a000000, v155
	v_mul_f32_e32 v229, 0x4b800000, v228
	v_cmp_gt_f32_e32 vcc, s51, v228
	v_add_u32_e32 v156, 0x90, v146
	s_nop 0
	v_cndmask_b32_e32 v228, v228, v229, vcc
	v_mad_u32_u24 v160, v156, s52, v134
	v_rsq_f32_e32 v228, v228
	s_nop 0
	v_mul_f32_e32 v229, 0x45800000, v228
	s_nop 0
	v_cndmask_b32_e32 v228, v228, v229, vcc
	v_pk_mul_f32 v[46:47], v[46:47], v[228:229] op_sel_hi:[1,0]
	v_pk_mul_f32 v[48:49], v[48:49], v[228:229] op_sel_hi:[1,0]
	v_pk_mul_f32 v[42:43], v[42:43], v[228:229] op_sel_hi:[1,0]
	v_pk_mul_f32 v[44:45], v[44:45], v[228:229] op_sel_hi:[1,0]
	v_pk_mul_f32 v[38:39], v[38:39], v[228:229] op_sel_hi:[1,0]
	v_pk_mul_f32 v[40:41], v[40:41], v[228:229] op_sel_hi:[1,0]
	v_pk_mul_f32 v[34:35], v[34:35], v[228:229] op_sel_hi:[1,0]
	v_pk_mul_f32 v[36:37], v[36:37], v[228:229] op_sel_hi:[1,0]
	v_pk_mul_f32 v[220:221], v[46:47], s[36:37]
	v_pk_mul_f32 v[222:223], v[48:49], s[36:37]
	v_pk_mul_f32 v[224:225], v[42:43], s[36:37]
	v_pk_mul_f32 v[226:227], v[44:45], s[36:37]
	v_exp_f32_e32 v220, v220
	v_exp_f32_e32 v221, v221
	v_exp_f32_e32 v222, v222
	v_exp_f32_e32 v223, v223
	v_exp_f32_e32 v224, v224
	v_exp_f32_e32 v225, v225
	v_exp_f32_e32 v226, v226
	v_exp_f32_e32 v227, v227
	v_pk_add_f32 v[220:221], v[220:221], s[38:39]
	v_pk_add_f32 v[222:223], v[222:223], s[38:39]
	v_pk_add_f32 v[224:225], v[224:225], s[38:39]
	v_pk_add_f32 v[226:227], v[226:227], s[38:39]
	v_rcp_f32_e32 v220, v220
	v_rcp_f32_e32 v221, v221
	v_rcp_f32_e32 v222, v222
	v_rcp_f32_e32 v223, v223
	v_rcp_f32_e32 v224, v224
	v_rcp_f32_e32 v225, v225
	v_rcp_f32_e32 v226, v226
	v_rcp_f32_e32 v227, v227
	v_pk_mul_f32 v[46:47], v[46:47], v[220:221]
	v_pk_mul_f32 v[48:49], v[48:49], v[222:223]
	v_pk_mul_f32 v[42:43], v[42:43], v[224:225]
	v_pk_mul_f32 v[44:45], v[44:45], v[226:227]
	v_pk_mul_f32 v[38:39], v[38:39], v[46:47]
	v_pk_mul_f32 v[40:41], v[40:41], v[48:49]
	v_pk_mul_f32 v[34:35], v[34:35], v[42:43]
	v_pk_mul_f32 v[36:37], v[36:37], v[44:45]
	v_cvt_pk_bf16_f32 v46, v38, v39
	v_cvt_pk_bf16_f32 v47, v40, v41
	v_cvt_pk_bf16_f32 v48, v34, v35
	v_cvt_pk_bf16_f32 v49, v36, v37
	global_store_dwordx4 v160, v[46:49], s[98:99] nt
	v_fmamk_f32 v228, v148, 0x3a000000, v155
	v_mul_f32_e32 v229, 0x4b800000, v228
	v_cmp_gt_f32_e32 vcc, s51, v228
	v_add_u32_e32 v156, 0xa0, v146
	s_nop 0
	v_cndmask_b32_e32 v228, v228, v229, vcc
	v_mad_u32_u24 v157, v156, s52, v134
	v_rsq_f32_e32 v228, v228
	s_nop 0
	v_mul_f32_e32 v229, 0x45800000, v228
	s_nop 0
	v_cndmask_b32_e32 v228, v228, v229, vcc
	v_pk_mul_f32 v[30:31], v[30:31], v[228:229] op_sel_hi:[1,0]
	v_pk_mul_f32 v[32:33], v[32:33], v[228:229] op_sel_hi:[1,0]
	v_pk_mul_f32 v[26:27], v[26:27], v[228:229] op_sel_hi:[1,0]
	v_pk_mul_f32 v[28:29], v[28:29], v[228:229] op_sel_hi:[1,0]
	v_pk_mul_f32 v[22:23], v[22:23], v[228:229] op_sel_hi:[1,0]
	v_pk_mul_f32 v[24:25], v[24:25], v[228:229] op_sel_hi:[1,0]
	v_pk_mul_f32 v[18:19], v[18:19], v[228:229] op_sel_hi:[1,0]
	v_pk_mul_f32 v[20:21], v[20:21], v[228:229] op_sel_hi:[1,0]
	v_pk_mul_f32 v[220:221], v[30:31], s[36:37]
	v_pk_mul_f32 v[222:223], v[32:33], s[36:37]
	v_pk_mul_f32 v[224:225], v[26:27], s[36:37]
	v_pk_mul_f32 v[226:227], v[28:29], s[36:37]
	v_exp_f32_e32 v220, v220
	v_exp_f32_e32 v221, v221
	v_exp_f32_e32 v222, v222
	v_exp_f32_e32 v223, v223
	v_exp_f32_e32 v224, v224
	v_exp_f32_e32 v225, v225
	v_exp_f32_e32 v226, v226
	v_exp_f32_e32 v227, v227
	v_pk_add_f32 v[220:221], v[220:221], s[38:39]
	v_pk_add_f32 v[222:223], v[222:223], s[38:39]
	v_pk_add_f32 v[224:225], v[224:225], s[38:39]
	v_pk_add_f32 v[226:227], v[226:227], s[38:39]
	v_rcp_f32_e32 v220, v220
	v_rcp_f32_e32 v221, v221
	v_rcp_f32_e32 v222, v222
	v_rcp_f32_e32 v223, v223
	v_rcp_f32_e32 v224, v224
	v_rcp_f32_e32 v225, v225
	v_rcp_f32_e32 v226, v226
	v_rcp_f32_e32 v227, v227
	v_pk_mul_f32 v[30:31], v[30:31], v[220:221]
	v_pk_mul_f32 v[32:33], v[32:33], v[222:223]
	v_pk_mul_f32 v[26:27], v[26:27], v[224:225]
	v_pk_mul_f32 v[28:29], v[28:29], v[226:227]
	v_pk_mul_f32 v[22:23], v[22:23], v[30:31]
	v_pk_mul_f32 v[24:25], v[24:25], v[32:33]
	v_pk_mul_f32 v[18:19], v[18:19], v[26:27]
	v_pk_mul_f32 v[20:21], v[20:21], v[28:29]
	v_cvt_pk_bf16_f32 v30, v22, v23
	v_cvt_pk_bf16_f32 v31, v24, v25
	v_cvt_pk_bf16_f32 v32, v18, v19
	v_cvt_pk_bf16_f32 v33, v20, v21
	global_store_dwordx4 v157, v[30:33], s[98:99] nt
	v_fmamk_f32 v228, v147, 0x3a000000, v155
	v_mul_f32_e32 v229, 0x4b800000, v228
	v_cmp_gt_f32_e32 vcc, s51, v228
	v_add_u32_e32 v156, 0xb0, v146
	s_nop 0
	v_cndmask_b32_e32 v228, v228, v229, vcc
	v_mad_u32_u24 v160, v156, s52, v134
	v_rsq_f32_e32 v228, v228
	s_nop 0
	v_mul_f32_e32 v229, 0x45800000, v228
	s_nop 0
	v_cndmask_b32_e32 v228, v228, v229, vcc
	v_pk_mul_f32 v[14:15], v[14:15], v[228:229] op_sel_hi:[1,0]
	v_pk_mul_f32 v[16:17], v[16:17], v[228:229] op_sel_hi:[1,0]
	v_pk_mul_f32 v[10:11], v[10:11], v[228:229] op_sel_hi:[1,0]
	v_pk_mul_f32 v[12:13], v[12:13], v[228:229] op_sel_hi:[1,0]
	v_pk_mul_f32 v[6:7], v[6:7], v[228:229] op_sel_hi:[1,0]
	v_pk_mul_f32 v[8:9], v[8:9], v[228:229] op_sel_hi:[1,0]
	v_pk_mul_f32 v[2:3], v[2:3], v[228:229] op_sel_hi:[1,0]
	v_pk_mul_f32 v[4:5], v[4:5], v[228:229] op_sel_hi:[1,0]
	v_pk_mul_f32 v[220:221], v[14:15], s[36:37]
	v_pk_mul_f32 v[222:223], v[16:17], s[36:37]
	v_pk_mul_f32 v[224:225], v[10:11], s[36:37]
	v_pk_mul_f32 v[226:227], v[12:13], s[36:37]
	v_exp_f32_e32 v220, v220
	v_exp_f32_e32 v221, v221
	v_exp_f32_e32 v222, v222
	v_exp_f32_e32 v223, v223
	v_exp_f32_e32 v224, v224
	v_exp_f32_e32 v225, v225
	v_exp_f32_e32 v226, v226
	v_exp_f32_e32 v227, v227
	v_pk_add_f32 v[220:221], v[220:221], s[38:39]
	v_pk_add_f32 v[222:223], v[222:223], s[38:39]
	v_pk_add_f32 v[224:225], v[224:225], s[38:39]
	v_pk_add_f32 v[226:227], v[226:227], s[38:39]
	v_rcp_f32_e32 v220, v220
	v_rcp_f32_e32 v221, v221
	v_rcp_f32_e32 v222, v222
	v_rcp_f32_e32 v223, v223
	v_rcp_f32_e32 v224, v224
	v_rcp_f32_e32 v225, v225
	v_rcp_f32_e32 v226, v226
	v_rcp_f32_e32 v227, v227
	v_pk_mul_f32 v[14:15], v[14:15], v[220:221]
	v_pk_mul_f32 v[16:17], v[16:17], v[222:223]
	v_pk_mul_f32 v[10:11], v[10:11], v[224:225]
	v_pk_mul_f32 v[12:13], v[12:13], v[226:227]
	v_pk_mul_f32 v[6:7], v[6:7], v[14:15]
	v_pk_mul_f32 v[8:9], v[8:9], v[16:17]
	v_pk_mul_f32 v[2:3], v[2:3], v[10:11]
	v_pk_mul_f32 v[4:5], v[4:5], v[12:13]
	v_cvt_pk_bf16_f32 v14, v6, v7
	v_cvt_pk_bf16_f32 v15, v8, v9
	v_cvt_pk_bf16_f32 v16, v2, v3
	v_cvt_pk_bf16_f32 v17, v4, v5
	s_andn2_b64 vcc, exec, s[18:19]
	s_mov_b64 s[18:19], -1
	global_store_dwordx4 v160, v[14:17], s[98:99] nt
	s_cbranch_vccnz .LBB0_995
; #define PG8_BAR __builtin_amdgcn_s_barrier()
; template <class Sched, class Epi>
; __device__ __forceinline__ void gemm_run(LAS unsigned char* lds, const Sched& S, const Epi& E) {
;     ...
;         }
;         if (wr == 0) PG8_BAR;
;         if constexpr (!Epi::AFTER_DRAIN) E(acc, cur, wr, wc, fr, fq);
;         if (!has_next) break;
; #pragma unroll
;         for (int a = 0; a < 2; ++a)
; #pragma unroll
;             for (int b = 0; b < 2; ++b)
; #pragma unroll
;                 for (int m = 0; m < 4; ++m)
; #pragma unroll
;                     for (int n = 0; n < 2; ++n) acc[a][b][m][n] = (f32x4){0.f, 0.f, 0.f, 0.f};
;         cur = nxt; cA = nA; cB = nB; lda = nlda; ldb = nldb; ++ui;
;         if (wr == 1) PG8_BAR;
;     }
	s_andn2_b64 vcc, exec, s[4:5]
	s_cbranch_vccnz .LBB0_994
	s_barrier
	s_branch .LBB0_994
